# NA loop: active-tile test done with one scalar compare instead of v_cndmask + v_readfirstlane + s_bitcmp (on top of the NA bias-add simplification)
# baseline (speedup 1.0000x reference)
; #define LAS __attribute__((address_space(3)))
; template <int KIND> ...
;     ...
;         for (int t = 0; t < nt; ++t) {
;             if (t + 1 < nt) ATT_LOAD(t + 1);
;             bool active = true;
;             if (KIND == 0 && t < n1) { const int kr = kr_lo + t; active = (kr >= rs_w) && (kr < rs_w + 8); }
;             if (__builtin_amdgcn_readfirstlane((int)active)) {
;                 const int buf = t & 1;
;                 bf16x8 kf[8];
; #pragma unroll
;                 for (int t4 = 0; t4 < 4; ++t4) { kf[2 * t4] = *(const LAS bf16x8*)(lds + buf * KBUF + koff + 32 * t4); kf[2 * t4 + 1] = *(const LAS bf16x8*)(lds + buf * KBUF + koff + 32 * KSTR + 32 * t4); }
;                 __builtin_amdgcn_sched_barrier(0);
;                 f32x16 s0, s1;
; #pragma unroll
;                 for (int t4 = 0; t4 < 4; ++t4) {
;                     s0 = __builtin_amdgcn_mfma_f32_32x32x16_bf16(kf[2 * t4], qf[t4], t4 == 0 ? mneg : s0, 0, 0, 0);
;                     s1 = __builtin_amdgcn_mfma_f32_32x32x16_bf16(kf[2 * t4 + 1], qf[t4], t4 == 0 ? mneg : s1, 0, 0, 0);
;                 }
;                 float ab0[16], ab1[16];
;                 const bool na_lat = (KIND == 0) && (t < n1);
;                 if (na_lat) {
;                     const int bo = boff0 + (kr_lo + t - qr + 7) * 124;
; #pragma unroll
;                     for (int j = 0; j < 16; ++j) {
;                         const int C0 = 8 * (j >> 2) + (j & 3), C1 = 32 + C0;
;                         const float b0 = *(const LAS float*)(lds + bo + 4 * C0), b1 = *(const LAS float*)(lds + bo + 4 * C1);
;                         ab0[j] = ((unsigned)(wb + C0) < 16u) ? b0 : -1e30f;
;                         ab1[j] = ((unsigned)(wb + C1) < 16u) ? b1 : -1e30f;
;                     }
.LBB0_147:
	s_cmp_lt_i32 s83, s80
	s_cselect_b64 s[78:79], -1, 0
	s_cmp_ge_i32 s83, s80
	s_cselect_b64 vcc, -1, 0
	s_add_i32 s10, s74, s83
	s_cmp_ge_i32 s10, s75
	s_cselect_b64 s[8:9], -1, 0
	s_cmp_lt_i32 s10, s76
	s_cselect_b64 s[10:11], -1, 0
	s_and_b64 s[8:9], s[8:9], s[10:11]
	s_or_b64 s[8:9], vcc, s[8:9]
	s_cmp_eq_u64 s[8:9], 0
	s_cbranch_scc1 .LBB0_162
	s_and_b32 s83, s83, 1
	s_mul_i32 s8, s83, 0x2400
	v_add_u32_e32 v68, s8, v212
	ds_read_b128 v[64:67], v68
	ds_read_b128 v[80:83], v68 offset:32
	ds_read_b128 v[84:87], v68 offset:4608
	ds_read_b128 v[88:91], v68 offset:4640
	ds_read_b128 v[92:95], v68 offset:64
	ds_read_b128 v[136:139], v68 offset:96
	ds_read_b128 v[140:143], v68 offset:4672
	ds_read_b128 v[144:147], v68 offset:4704
	s_waitcnt lgkmcnt(7)
	v_mfma_f32_32x32x16_bf16 v[96:111], v[64:67], v[112:115], v[48:63]
	s_andn2_b64 vcc, exec, s[78:79]
	s_waitcnt lgkmcnt(5)
	v_mfma_f32_32x32x16_bf16 v[64:79], v[84:87], v[112:115], v[48:63]
	v_mfma_f32_32x32x16_bf16 v[96:111], v[80:83], v[116:119], v[96:111]
	s_waitcnt lgkmcnt(4)
	v_mfma_f32_32x32x16_bf16 v[64:79], v[88:91], v[116:119], v[64:79]
	s_waitcnt lgkmcnt(3)
	v_mfma_f32_32x32x16_bf16 v[96:111], v[92:95], v[120:123], v[96:111]
	s_waitcnt lgkmcnt(1)
	v_mfma_f32_32x32x16_bf16 v[64:79], v[140:143], v[120:123], v[64:79]
	v_mfma_f32_32x32x16_bf16 v[96:111], v[136:139], v[124:127], v[96:111]
	s_waitcnt lgkmcnt(0)
	v_mfma_f32_32x32x16_bf16 v[64:79], v[144:147], v[124:127], v[64:79]
	s_cbranch_vccnz .LBB0_150
	ds_read2_b32 v[80:81], v237 offset0:32 offset1:33
	ds_read2_b32 v[82:83], v237 offset1:1
	ds_read2_b32 v[84:85], v237 offset0:2 offset1:3
	ds_read2_b32 v[86:87], v237 offset0:34 offset1:35
	v_readlane_b32 s8, v255, 33
	v_readlane_b32 s9, v255, 34
	s_waitcnt lgkmcnt(2)
	v_cndmask_b32_e64 v163, v229, v83, s[12:13]
	v_cndmask_b32_e64 v160, v229, v81, s[14:15]
	v_cndmask_b32_e64 v236, v229, v80, s[8:9]
	v_readlane_b32 s8, v255, 35
	v_readlane_b32 s9, v255, 36
	s_waitcnt lgkmcnt(1)
	v_cndmask_b32_e64 v165, v229, v85, s[16:17]
	v_cndmask_b32_e64 v164, v229, v84, s[18:19]
	v_cndmask_b32_e64 v162, v229, v82, s[8:9]
	s_waitcnt lgkmcnt(0)
	v_cndmask_b32_e64 v167, v229, v87, s[20:21]
	v_cndmask_b32_e64 v166, v229, v86, s[22:23]
	ds_read2_b32 v[80:81], v237 offset0:8 offset1:9
	ds_read2_b32 v[82:83], v237 offset0:40 offset1:41
	ds_read2_b32 v[84:85], v237 offset0:10 offset1:11
	ds_read2_b32 v[86:87], v237 offset0:42 offset1:43
	s_waitcnt lgkmcnt(3)
	v_cndmask_b32_e64 v171, v229, v81, s[24:25]
	v_cndmask_b32_e64 v170, v229, v80, s[26:27]
	s_waitcnt lgkmcnt(2)
	v_cndmask_b32_e64 v169, v229, v83, s[28:29]
	v_cndmask_b32_e64 v168, v229, v82, s[30:31]
	s_waitcnt lgkmcnt(1)
	v_cndmask_b32_e64 v175, v229, v85, s[34:35]
	v_cndmask_b32_e64 v174, v229, v84, s[36:37]
	s_waitcnt lgkmcnt(0)
	v_cndmask_b32_e64 v173, v229, v87, s[38:39]
	v_cndmask_b32_e64 v172, v229, v86, s[40:41]
	ds_read2_b32 v[80:81], v237 offset0:48 offset1:49
	ds_read2_b32 v[82:83], v237 offset0:16 offset1:17
	ds_read2_b32 v[84:85], v237 offset0:18 offset1:19
	ds_read2_b32 v[86:87], v237 offset0:50 offset1:51
	s_waitcnt lgkmcnt(3)
	v_cndmask_b32_e64 v177, v229, v80, s[42:43]
	s_waitcnt lgkmcnt(2)
	v_cndmask_b32_e64 v183, v229, v83, s[46:47]
	v_cndmask_b32_e64 v182, v229, v82, s[44:45]
	v_cndmask_b32_e64 v178, v229, v81, s[48:49]
	s_waitcnt lgkmcnt(1)
	v_cndmask_b32_e64 v185, v229, v85, s[50:51]
	v_cndmask_b32_e64 v184, v229, v84, s[52:53]
	s_waitcnt lgkmcnt(0)
	v_cndmask_b32_e64 v181, v229, v87, s[54:55]
	v_cndmask_b32_e64 v180, v229, v86, s[56:57]
	ds_read2_b32 v[80:81], v237 offset0:24 offset1:25
	ds_read2_b32 v[82:83], v237 offset0:56 offset1:57
	ds_read2_b32 v[84:85], v237 offset0:26 offset1:27
	ds_read2_b32 v[86:87], v237 offset0:58 offset1:59
	s_waitcnt lgkmcnt(3)
	v_cndmask_b32_e64 v189, v229, v81, s[58:59]
	v_cndmask_b32_e64 v188, v229, v80, s[60:61]
	s_waitcnt lgkmcnt(2)
	v_cndmask_b32_e64 v187, v229, v83, s[62:63]
	v_cndmask_b32_e64 v186, v229, v82, s[64:65]
	s_waitcnt lgkmcnt(1)
	v_cndmask_b32_e64 v201, v229, v85, s[66:67]
	v_cndmask_b32_e64 v200, v229, v84, s[68:69]
	s_waitcnt lgkmcnt(0)
	v_cndmask_b32_e64 v191, v229, v87, s[70:71]
	v_cndmask_b32_e64 v190, v229, v86, s[72:73]
